# diff-attention key loop on v_mfma_f32_16x16x32_bf16 (5 fragment tuples) together with the mixA work rebalance
# baseline (speedup 1.0000x reference)
.LBB0_555:
	v_lshlrev_b32_e32 v2, 1, v2
	v_lshlrev_b32_e32 v160, 1, v160
	v_lshlrev_b32_e32 v158, 1, v158
	v_lshlrev_b32_e32 v156, 1, v156
	v_lshlrev_b32_e32 v244, 1, v10
	v_lshlrev_b32_e32 v245, 1, v8
	v_lshlrev_b32_e32 v246, 1, v6
	v_lshlrev_b32_e32 v249, 1, v4
	v_mov_b32_e32 v157, 0
	v_mov_b32_e32 v159, v149
	v_lshl_add_u32 v167, v167, 1, v178
	v_lshl_add_u32 v182, v182, 1, v178
	v_lshl_add_u32 v187, v187, 1, v178
	v_lshl_add_u32 v170, v170, 1, v178
	v_add_u32_e32 v169, v169, v180
	v_add_u32_e32 v185, v185, v180
	v_add_u32_e32 v190, v190, v180
	v_add_u32_e32 v172, v172, v180
	v_bfe_u32 v250, v1, 4, 2
	v_lshrrev_b32_e32 v13, 1, v250
	v_sub_u32_e32 v13, v250, v13
	v_lshlrev_b32_e32 v13, 4, v13
	v_and_b32_e32 v250, 1, v250
	v_mul_u32_u24_e32 v207, 0x900, v250
	v_sub_u32_e32 v206, v13, v207
	v_add_u32_e32 v206, v206, v174
	v_add_u32_e32 v206, 0x2400, v206
	v_bfe_u32 v207, v1, 3, 1
	v_lshlrev_b32_e32 v207, 3, v207
	v_lshlrev_b32_e32 v250, 4, v250
	v_sub_u32_e32 v207, v207, v250
	v_mul_i32_i24_e32 v207, 0x110, v207
	v_add3_u32 v205, v207, v13, v173
	s_waitcnt vmcnt(0)
	v_and_b32_e32 v250, 15, v1
	v_bfe_u32 v13, v1, 4, 1
	v_lshl_add_u32 v250, v13, 5, v250
	v_lshlrev_b32_e32 v250, 2, v250
	v_add_u32_e32 v13, 64, v250
	v_and_b32_e32 v207, 32, v1
	v_cmp_ne_u32_e32 vcc, 0, v207
	ds_bpermute_b32 v4, v250, v126
	ds_bpermute_b32 v5, v250, v122
	ds_bpermute_b32 v6, v13, v126
	ds_bpermute_b32 v7, v13, v122
	s_waitcnt lgkmcnt(0)
	v_cndmask_b32_e32 v126, v4, v5, vcc
	v_cndmask_b32_e32 v122, v6, v7, vcc
	ds_bpermute_b32 v4, v250, v127
	ds_bpermute_b32 v5, v250, v123
	ds_bpermute_b32 v6, v13, v127
	ds_bpermute_b32 v7, v13, v123
	s_waitcnt lgkmcnt(0)
	v_cndmask_b32_e32 v127, v4, v5, vcc
	v_cndmask_b32_e32 v123, v6, v7, vcc
	ds_bpermute_b32 v4, v250, v128
	ds_bpermute_b32 v5, v250, v124
	ds_bpermute_b32 v6, v13, v128
	ds_bpermute_b32 v7, v13, v124
	s_waitcnt lgkmcnt(0)
	v_cndmask_b32_e32 v128, v4, v5, vcc
	v_cndmask_b32_e32 v124, v6, v7, vcc
	ds_bpermute_b32 v4, v250, v129
	ds_bpermute_b32 v5, v250, v125
	ds_bpermute_b32 v6, v13, v129
	ds_bpermute_b32 v7, v13, v125
	s_waitcnt lgkmcnt(0)
	v_cndmask_b32_e32 v129, v4, v5, vcc
	v_cndmask_b32_e32 v125, v6, v7, vcc
	ds_bpermute_b32 v4, v250, v118
	ds_bpermute_b32 v5, v250, v114
	ds_bpermute_b32 v6, v13, v118
	ds_bpermute_b32 v7, v13, v114
	s_waitcnt lgkmcnt(0)
	v_cndmask_b32_e32 v118, v4, v5, vcc
	v_cndmask_b32_e32 v114, v6, v7, vcc
	ds_bpermute_b32 v4, v250, v119
	ds_bpermute_b32 v5, v250, v115
	ds_bpermute_b32 v6, v13, v119
	ds_bpermute_b32 v7, v13, v115
	s_waitcnt lgkmcnt(0)
	v_cndmask_b32_e32 v119, v4, v5, vcc
	v_cndmask_b32_e32 v115, v6, v7, vcc
	ds_bpermute_b32 v4, v250, v120
	ds_bpermute_b32 v5, v250, v116
	ds_bpermute_b32 v6, v13, v120
	ds_bpermute_b32 v7, v13, v116
	s_waitcnt lgkmcnt(0)
	v_cndmask_b32_e32 v120, v4, v5, vcc
	v_cndmask_b32_e32 v116, v6, v7, vcc
	ds_bpermute_b32 v4, v250, v121
	ds_bpermute_b32 v5, v250, v117
	ds_bpermute_b32 v6, v13, v121
	ds_bpermute_b32 v7, v13, v117
	s_waitcnt lgkmcnt(0)
	v_cndmask_b32_e32 v121, v4, v5, vcc
	v_cndmask_b32_e32 v117, v6, v7, vcc

.Ldq0_p0_addr:
	global_load_dwordx4 v[212:215], v2, s[24:25]
	global_load_dwordx4 v[216:219], v244, s[20:21]
	global_load_dwordx4 v[220:223], v160, s[24:25]
	global_load_dwordx4 v[224:227], v245, s[20:21]
	global_load_dwordx4 v[228:231], v158, s[24:25]
	global_load_dwordx4 v[232:235], v246, s[20:21]
	global_load_dwordx4 v[236:239], v156, s[24:25]
	global_load_dwordx4 v[240:243], v249, s[20:21]
	ds_read_b128 v[4:7], v205
	ds_read_b128 v[8:11], v205 offset:2176
	ds_read_b128 v[14:17], v205 offset:8704
	ds_read_b128 v[208:211], v205 offset:10880
	ds_read_b128 v[252:255], v205 offset:64
	s_waitcnt vmcnt(8)
	s_waitcnt lgkmcnt(4)
	v_mfma_f32_16x16x32_bf16 v[98:101], v[4:7], v[126:129], 0
	v_mfma_f32_16x16x32_bf16 v[106:109], v[4:7], v[122:125], 0
	ds_read_b128 v[4:7], v205 offset:2240
	s_waitcnt lgkmcnt(4)
	v_mfma_f32_16x16x32_bf16 v[102:105], v[8:11], v[126:129], 0
	v_mfma_f32_16x16x32_bf16 v[110:113], v[8:11], v[122:125], 0
	ds_read_b128 v[8:11], v205 offset:8768
	s_waitcnt lgkmcnt(4)
	v_mfma_f32_16x16x32_bf16 v[82:85], v[14:17], v[126:129], 0
	v_mfma_f32_16x16x32_bf16 v[90:93], v[14:17], v[122:125], 0
	ds_read_b128 v[14:17], v205 offset:10944
	s_waitcnt lgkmcnt(4)
	v_mfma_f32_16x16x32_bf16 v[86:89], v[208:211], v[126:129], 0
	v_mfma_f32_16x16x32_bf16 v[94:97], v[208:211], v[122:125], 0
	ds_read_b128 v[208:211], v206 offset:25600
	s_waitcnt lgkmcnt(4)
	v_mfma_f32_16x16x32_bf16 v[98:101], v[252:255], v[118:121], v[98:101]
	v_mfma_f32_16x16x32_bf16 v[106:109], v[252:255], v[114:117], v[106:109]
	ds_read_b128 v[252:255], v206 offset:27904
	s_waitcnt lgkmcnt(4)
	v_mfma_f32_16x16x32_bf16 v[102:105], v[4:7], v[118:121], v[102:105]
	v_mfma_f32_16x16x32_bf16 v[110:113], v[4:7], v[114:117], v[110:113]
	ds_read_b128 v[4:7], v206 offset:30208
	s_waitcnt lgkmcnt(4)
	v_mfma_f32_16x16x32_bf16 v[82:85], v[8:11], v[118:121], v[82:85]
	v_mfma_f32_16x16x32_bf16 v[90:93], v[8:11], v[114:117], v[90:93]
	ds_read_b128 v[8:11], v206 offset:32512
	s_waitcnt lgkmcnt(4)
	v_mfma_f32_16x16x32_bf16 v[86:89], v[14:17], v[118:121], v[86:89]
	v_mfma_f32_16x16x32_bf16 v[94:97], v[14:17], v[114:117], v[94:97]
	ds_read_b128 v[14:17], v206 offset:34816
	s_nop 7
	s_nop 1
	v_max3_f32 v207, v98, v99, v100
	v_max3_f32 v207, v207, v101, v102
	v_max3_f32 v207, v207, v103, v104
	v_max3_f32 v207, v207, v105, v82
	v_max3_f32 v207, v207, v83, v84
	v_max3_f32 v207, v207, v85, v86
	v_max3_f32 v207, v207, v87, v88
	v_max3_f32 v207, v207, v89, v89
	v_max3_f32 v13, v106, v107, v108
	v_max3_f32 v13, v13, v109, v110
	v_max3_f32 v13, v13, v111, v112
	v_max3_f32 v13, v13, v113, v90
	v_max3_f32 v13, v13, v91, v92
	v_max3_f32 v13, v13, v93, v94
	v_max3_f32 v13, v13, v95, v96
	v_max3_f32 v13, v13, v97, v97
	s_nop 1
	v_permlane32_swap_b32_e32 v207, v13
	v_max_f32_e32 v207, v207, v13
	v_mov_b32_e32 v13, v207
	s_nop 1
	v_permlane16_swap_b32_e32 v207, v13
	v_max_f32_e32 v207, v207, v13
	v_mov_b32_e32 v13, v207
	s_nop 1
	v_permlane32_swap_b32_e32 v207, v13
	v_add_f32_e32 v250, 0x41000000, v149
	v_cmp_gt_f32_e32 vcc, v207, v250
	s_cbranch_vccnz .Ldq0_p0_resc
	v_add_f32_e32 v250, 0x41000000, v159
	v_cmp_gt_f32_e32 vcc, v13, v250
	s_cbranch_vccz .Ldq0_p0_nores
.Ldq0_p0_resc:
	v_max_f32_e32 v207, v149, v207
	v_sub_f32_e32 v250, v149, v207
	v_exp_f32_e32 v250, v250
	v_mov_b32_e32 v149, v207
	v_pk_mul_f32 v[66:67], v[66:67], v[250:251] op_sel_hi:[1,0]
	v_pk_mul_f32 v[68:69], v[68:69], v[250:251] op_sel_hi:[1,0]
	v_pk_mul_f32 v[74:75], v[74:75], v[250:251] op_sel_hi:[1,0]
	v_pk_mul_f32 v[76:77], v[76:77], v[250:251] op_sel_hi:[1,0]
	v_pk_mul_f32 v[50:51], v[50:51], v[250:251] op_sel_hi:[1,0]
	v_pk_mul_f32 v[52:53], v[52:53], v[250:251] op_sel_hi:[1,0]
	v_pk_mul_f32 v[58:59], v[58:59], v[250:251] op_sel_hi:[1,0]
	v_pk_mul_f32 v[60:61], v[60:61], v[250:251] op_sel_hi:[1,0]
	v_pk_mul_f32 v[34:35], v[34:35], v[250:251] op_sel_hi:[1,0]
	v_pk_mul_f32 v[36:37], v[36:37], v[250:251] op_sel_hi:[1,0]
	v_pk_mul_f32 v[42:43], v[42:43], v[250:251] op_sel_hi:[1,0]
	v_pk_mul_f32 v[44:45], v[44:45], v[250:251] op_sel_hi:[1,0]
	v_pk_mul_f32 v[18:19], v[18:19], v[250:251] op_sel_hi:[1,0]
	v_pk_mul_f32 v[20:21], v[20:21], v[250:251] op_sel_hi:[1,0]
	v_pk_mul_f32 v[26:27], v[26:27], v[250:251] op_sel_hi:[1,0]
	v_pk_mul_f32 v[28:29], v[28:29], v[250:251] op_sel_hi:[1,0]
	v_mul_f32_e32 v12, v12, v250
	v_max_f32_e32 v13, v159, v13
	v_sub_f32_e32 v250, v159, v13
	v_exp_f32_e32 v250, v250
	v_mov_b32_e32 v159, v13
	v_pk_mul_f32 v[70:71], v[70:71], v[250:251] op_sel_hi:[1,0]
	v_pk_mul_f32 v[72:73], v[72:73], v[250:251] op_sel_hi:[1,0]
	v_pk_mul_f32 v[78:79], v[78:79], v[250:251] op_sel_hi:[1,0]
	v_pk_mul_f32 v[80:81], v[80:81], v[250:251] op_sel_hi:[1,0]
	v_pk_mul_f32 v[54:55], v[54:55], v[250:251] op_sel_hi:[1,0]
	v_pk_mul_f32 v[56:57], v[56:57], v[250:251] op_sel_hi:[1,0]
	v_pk_mul_f32 v[62:63], v[62:63], v[250:251] op_sel_hi:[1,0]
	v_pk_mul_f32 v[64:65], v[64:65], v[250:251] op_sel_hi:[1,0]
	v_pk_mul_f32 v[38:39], v[38:39], v[250:251] op_sel_hi:[1,0]
	v_pk_mul_f32 v[40:41], v[40:41], v[250:251] op_sel_hi:[1,0]
	v_pk_mul_f32 v[46:47], v[46:47], v[250:251] op_sel_hi:[1,0]
	v_pk_mul_f32 v[48:49], v[48:49], v[250:251] op_sel_hi:[1,0]
	v_pk_mul_f32 v[22:23], v[22:23], v[250:251] op_sel_hi:[1,0]
	v_pk_mul_f32 v[24:25], v[24:25], v[250:251] op_sel_hi:[1,0]
	v_pk_mul_f32 v[30:31], v[30:31], v[250:251] op_sel_hi:[1,0]
	v_pk_mul_f32 v[32:33], v[32:33], v[250:251] op_sel_hi:[1,0]
	v_mul_f32_e32 v157, v157, v250
.Ldq0_p0_nores:
	v_sub_f32_e32 v98, v98, v149
	v_exp_f32_e32 v98, v98
	v_sub_f32_e32 v99, v99, v149
	v_exp_f32_e32 v99, v99
	v_sub_f32_e32 v100, v100, v149
	v_exp_f32_e32 v100, v100
	v_sub_f32_e32 v101, v101, v149
	v_exp_f32_e32 v101, v101
	v_sub_f32_e32 v102, v102, v149
	v_exp_f32_e32 v102, v102
	v_sub_f32_e32 v103, v103, v149
	v_exp_f32_e32 v103, v103
	v_sub_f32_e32 v104, v104, v149
	v_exp_f32_e32 v104, v104
	v_sub_f32_e32 v105, v105, v149
	v_exp_f32_e32 v105, v105
	v_add_f32_e32 v12, v12, v98
	v_add_f32_e32 v12, v12, v99
	v_add_f32_e32 v12, v12, v100
	v_add_f32_e32 v12, v12, v101
	v_add_f32_e32 v12, v12, v102
	v_add_f32_e32 v12, v12, v103
	v_add_f32_e32 v12, v12, v104
	v_add_f32_e32 v12, v12, v105
	v_cvt_pk_bf16_f32 v98, v98, v99
	v_cvt_pk_bf16_f32 v99, v100, v101
	v_cvt_pk_bf16_f32 v100, v102, v103
	v_cvt_pk_bf16_f32 v101, v104, v105
	v_sub_f32_e32 v106, v106, v159
	v_exp_f32_e32 v106, v106
	v_sub_f32_e32 v107, v107, v159
	v_exp_f32_e32 v107, v107
	v_sub_f32_e32 v108, v108, v159
	v_exp_f32_e32 v108, v108
	v_sub_f32_e32 v109, v109, v159
	v_exp_f32_e32 v109, v109
	v_sub_f32_e32 v110, v110, v159
	v_exp_f32_e32 v110, v110
	v_sub_f32_e32 v111, v111, v159
	v_exp_f32_e32 v111, v111
	v_sub_f32_e32 v112, v112, v159
	v_exp_f32_e32 v112, v112
	v_sub_f32_e32 v113, v113, v159
	v_exp_f32_e32 v113, v113
	v_add_f32_e32 v157, v157, v106
	v_add_f32_e32 v157, v157, v107
	v_add_f32_e32 v157, v157, v108
	v_add_f32_e32 v157, v157, v109
	v_add_f32_e32 v157, v157, v110
	v_add_f32_e32 v157, v157, v111
	v_add_f32_e32 v157, v157, v112
	v_add_f32_e32 v157, v157, v113
	v_cvt_pk_bf16_f32 v106, v106, v107
	v_cvt_pk_bf16_f32 v107, v108, v109
	v_cvt_pk_bf16_f32 v108, v110, v111
	v_cvt_pk_bf16_f32 v109, v112, v113
	s_nop 1
	s_waitcnt lgkmcnt(4)
	v_mfma_f32_16x16x32_bf16 v[66:69], v[208:211], v[98:101], v[66:69]
	v_mfma_f32_16x16x32_bf16 v[70:73], v[208:211], v[106:109], v[70:73]
	ds_read_b128 v[208:211], v206 offset:37120
	v_sub_f32_e32 v82, v82, v149
	v_exp_f32_e32 v82, v82
	v_sub_f32_e32 v83, v83, v149
	v_exp_f32_e32 v83, v83
	v_sub_f32_e32 v84, v84, v149
	v_exp_f32_e32 v84, v84
	v_sub_f32_e32 v85, v85, v149
	v_exp_f32_e32 v85, v85
	s_waitcnt lgkmcnt(4)
	v_mfma_f32_16x16x32_bf16 v[74:77], v[252:255], v[98:101], v[74:77]
	v_mfma_f32_16x16x32_bf16 v[78:81], v[252:255], v[106:109], v[78:81]
	ds_read_b128 v[252:255], v206 offset:39424
	v_sub_f32_e32 v86, v86, v149
	v_exp_f32_e32 v86, v86
	v_sub_f32_e32 v87, v87, v149
	v_exp_f32_e32 v87, v87
	v_sub_f32_e32 v88, v88, v149
	v_exp_f32_e32 v88, v88
	v_sub_f32_e32 v89, v89, v149
	v_exp_f32_e32 v89, v89
	s_waitcnt lgkmcnt(4)
	v_mfma_f32_16x16x32_bf16 v[50:53], v[4:7], v[98:101], v[50:53]
	v_mfma_f32_16x16x32_bf16 v[54:57], v[4:7], v[106:109], v[54:57]
	ds_read_b128 v[4:7], v206 offset:41728
	v_add_f32_e32 v12, v12, v82
	v_add_f32_e32 v12, v12, v83
	v_add_f32_e32 v12, v12, v84
	v_add_f32_e32 v12, v12, v85
	v_add_f32_e32 v12, v12, v86
	v_add_f32_e32 v12, v12, v87
	v_add_f32_e32 v12, v12, v88
	v_add_f32_e32 v12, v12, v89
	s_waitcnt lgkmcnt(4)
	v_mfma_f32_16x16x32_bf16 v[58:61], v[8:11], v[98:101], v[58:61]
	v_mfma_f32_16x16x32_bf16 v[62:65], v[8:11], v[106:109], v[62:65]
	ds_read_b128 v[8:11], v206 offset:25664
	v_cvt_pk_bf16_f32 v82, v82, v83
	v_cvt_pk_bf16_f32 v83, v84, v85
	v_cvt_pk_bf16_f32 v84, v86, v87
	v_cvt_pk_bf16_f32 v85, v88, v89
	v_sub_f32_e32 v90, v90, v159
	v_exp_f32_e32 v90, v90
	v_sub_f32_e32 v91, v91, v159
	v_exp_f32_e32 v91, v91
	s_waitcnt lgkmcnt(4)
	v_mfma_f32_16x16x32_bf16 v[34:37], v[14:17], v[98:101], v[34:37]
	v_mfma_f32_16x16x32_bf16 v[38:41], v[14:17], v[106:109], v[38:41]
	ds_read_b128 v[14:17], v206 offset:27968
	v_sub_f32_e32 v92, v92, v159
	v_exp_f32_e32 v92, v92
	v_sub_f32_e32 v93, v93, v159
	v_exp_f32_e32 v93, v93
	v_sub_f32_e32 v94, v94, v159
	v_exp_f32_e32 v94, v94
	v_sub_f32_e32 v95, v95, v159
	v_exp_f32_e32 v95, v95
	s_waitcnt lgkmcnt(4)
	v_mfma_f32_16x16x32_bf16 v[42:45], v[208:211], v[98:101], v[42:45]
	v_mfma_f32_16x16x32_bf16 v[46:49], v[208:211], v[106:109], v[46:49]
	ds_read_b128 v[208:211], v206 offset:30272
	v_sub_f32_e32 v96, v96, v159
	v_exp_f32_e32 v96, v96
	v_sub_f32_e32 v97, v97, v159
	v_exp_f32_e32 v97, v97
	v_add_f32_e32 v157, v157, v90
	v_add_f32_e32 v157, v157, v91
	v_add_f32_e32 v157, v157, v92
	v_add_f32_e32 v157, v157, v93
	s_waitcnt lgkmcnt(4)
	v_mfma_f32_16x16x32_bf16 v[18:21], v[252:255], v[98:101], v[18:21]
	v_mfma_f32_16x16x32_bf16 v[22:25], v[252:255], v[106:109], v[22:25]
	ds_read_b128 v[252:255], v206 offset:32576
	v_add_f32_e32 v157, v157, v94
	v_add_f32_e32 v157, v157, v95
	v_add_f32_e32 v157, v157, v96
	v_add_f32_e32 v157, v157, v97
	v_cvt_pk_bf16_f32 v90, v90, v91
	v_cvt_pk_bf16_f32 v91, v92, v93
	v_cvt_pk_bf16_f32 v92, v94, v95
	v_cvt_pk_bf16_f32 v93, v96, v97
	s_waitcnt lgkmcnt(4)
	v_mfma_f32_16x16x32_bf16 v[26:29], v[4:7], v[98:101], v[26:29]
	v_mfma_f32_16x16x32_bf16 v[30:33], v[4:7], v[106:109], v[30:33]
	ds_read_b128 v[4:7], v206 offset:34880
	s_waitcnt lgkmcnt(4)
	v_mfma_f32_16x16x32_bf16 v[66:69], v[8:11], v[82:85], v[66:69]
	v_mfma_f32_16x16x32_bf16 v[70:73], v[8:11], v[90:93], v[70:73]
	ds_read_b128 v[8:11], v206 offset:37184
	s_waitcnt lgkmcnt(4)
	v_mfma_f32_16x16x32_bf16 v[74:77], v[14:17], v[82:85], v[74:77]
	v_mfma_f32_16x16x32_bf16 v[78:81], v[14:17], v[90:93], v[78:81]
	ds_read_b128 v[14:17], v206 offset:39488
	s_waitcnt lgkmcnt(4)
	v_mfma_f32_16x16x32_bf16 v[50:53], v[208:211], v[82:85], v[50:53]
	v_mfma_f32_16x16x32_bf16 v[54:57], v[208:211], v[90:93], v[54:57]
	ds_read_b128 v[208:211], v206 offset:41792
	s_waitcnt vmcnt(7)
	ds_write_b128 v167, v[212:215] offset:17408
	s_waitcnt vmcnt(6)
	ds_write_b128 v169, v[216:219] offset:53248
	s_waitcnt lgkmcnt(6)
	v_mfma_f32_16x16x32_bf16 v[58:61], v[252:255], v[82:85], v[58:61]
	v_mfma_f32_16x16x32_bf16 v[62:65], v[252:255], v[90:93], v[62:65]
	s_waitcnt vmcnt(5)
	ds_write_b128 v182, v[220:223] offset:17408
	s_waitcnt vmcnt(4)
	ds_write_b128 v185, v[224:227] offset:53248
	s_waitcnt lgkmcnt(7)
	v_mfma_f32_16x16x32_bf16 v[34:37], v[4:7], v[82:85], v[34:37]
	v_mfma_f32_16x16x32_bf16 v[38:41], v[4:7], v[90:93], v[38:41]
	s_waitcnt vmcnt(3)
	ds_write_b128 v187, v[228:231] offset:17408
	s_waitcnt vmcnt(2)
	ds_write_b128 v190, v[232:235] offset:53248
	s_waitcnt lgkmcnt(8)
	v_mfma_f32_16x16x32_bf16 v[42:45], v[8:11], v[82:85], v[42:45]
	v_mfma_f32_16x16x32_bf16 v[46:49], v[8:11], v[90:93], v[46:49]
	s_waitcnt vmcnt(1)
	ds_write_b128 v170, v[236:239] offset:17408
	s_waitcnt vmcnt(0)
	ds_write_b128 v172, v[240:243] offset:53248
	s_waitcnt lgkmcnt(9)
	v_mfma_f32_16x16x32_bf16 v[18:21], v[14:17], v[82:85], v[18:21]
	v_mfma_f32_16x16x32_bf16 v[22:25], v[14:17], v[90:93], v[22:25]
	s_waitcnt lgkmcnt(8)
	v_mfma_f32_16x16x32_bf16 v[26:29], v[208:211], v[82:85], v[26:29]
	v_mfma_f32_16x16x32_bf16 v[30:33], v[208:211], v[90:93], v[30:33]
	s_waitcnt lgkmcnt(0)
	s_barrier
	s_cmp_eq_u32 s38, s41
	s_cbranch_scc1 .Ldq0_exit
	s_mov_b32 s42, s41

.Ldq0_p1_addr:
	global_load_dwordx4 v[212:215], v2, s[24:25]
	global_load_dwordx4 v[216:219], v244, s[20:21]
	global_load_dwordx4 v[220:223], v160, s[24:25]
	global_load_dwordx4 v[224:227], v245, s[20:21]
	global_load_dwordx4 v[228:231], v158, s[24:25]
	global_load_dwordx4 v[232:235], v246, s[20:21]
	global_load_dwordx4 v[236:239], v156, s[24:25]
	global_load_dwordx4 v[240:243], v249, s[20:21]
	ds_read_b128 v[4:7], v205 offset:17408
	ds_read_b128 v[8:11], v205 offset:19584
	ds_read_b128 v[14:17], v205 offset:26112
	ds_read_b128 v[208:211], v205 offset:28288
	ds_read_b128 v[252:255], v205 offset:17472
	s_waitcnt vmcnt(8)
	s_waitcnt lgkmcnt(4)
	v_mfma_f32_16x16x32_bf16 v[98:101], v[4:7], v[126:129], 0
	v_mfma_f32_16x16x32_bf16 v[106:109], v[4:7], v[122:125], 0
	ds_read_b128 v[4:7], v205 offset:19648
	s_waitcnt lgkmcnt(4)
	v_mfma_f32_16x16x32_bf16 v[102:105], v[8:11], v[126:129], 0
	v_mfma_f32_16x16x32_bf16 v[110:113], v[8:11], v[122:125], 0
	ds_read_b128 v[8:11], v205 offset:26176
	s_waitcnt lgkmcnt(4)
	v_mfma_f32_16x16x32_bf16 v[82:85], v[14:17], v[126:129], 0
	v_mfma_f32_16x16x32_bf16 v[90:93], v[14:17], v[122:125], 0
	ds_read_b128 v[14:17], v205 offset:28352
	s_waitcnt lgkmcnt(4)
	v_mfma_f32_16x16x32_bf16 v[86:89], v[208:211], v[126:129], 0
	v_mfma_f32_16x16x32_bf16 v[94:97], v[208:211], v[122:125], 0
	ds_read_b128 v[208:211], v206 offset:44032
	s_waitcnt lgkmcnt(4)
	v_mfma_f32_16x16x32_bf16 v[98:101], v[252:255], v[118:121], v[98:101]
	v_mfma_f32_16x16x32_bf16 v[106:109], v[252:255], v[114:117], v[106:109]
	ds_read_b128 v[252:255], v206 offset:46336
	s_waitcnt lgkmcnt(4)
	v_mfma_f32_16x16x32_bf16 v[102:105], v[4:7], v[118:121], v[102:105]
	v_mfma_f32_16x16x32_bf16 v[110:113], v[4:7], v[114:117], v[110:113]
	ds_read_b128 v[4:7], v206 offset:48640
	s_waitcnt lgkmcnt(4)
	v_mfma_f32_16x16x32_bf16 v[82:85], v[8:11], v[118:121], v[82:85]
	v_mfma_f32_16x16x32_bf16 v[90:93], v[8:11], v[114:117], v[90:93]
	ds_read_b128 v[8:11], v206 offset:50944
	s_waitcnt lgkmcnt(4)
	v_mfma_f32_16x16x32_bf16 v[86:89], v[14:17], v[118:121], v[86:89]
	v_mfma_f32_16x16x32_bf16 v[94:97], v[14:17], v[114:117], v[94:97]
	ds_read_b128 v[14:17], v206 offset:53248
	s_nop 7
	s_nop 1
	v_max3_f32 v207, v98, v99, v100
	v_max3_f32 v207, v207, v101, v102
	v_max3_f32 v207, v207, v103, v104
	v_max3_f32 v207, v207, v105, v82
	v_max3_f32 v207, v207, v83, v84
	v_max3_f32 v207, v207, v85, v86
	v_max3_f32 v207, v207, v87, v88
	v_max3_f32 v207, v207, v89, v89
	v_max3_f32 v13, v106, v107, v108
	v_max3_f32 v13, v13, v109, v110
	v_max3_f32 v13, v13, v111, v112
	v_max3_f32 v13, v13, v113, v90
	v_max3_f32 v13, v13, v91, v92
	v_max3_f32 v13, v13, v93, v94
	v_max3_f32 v13, v13, v95, v96
	v_max3_f32 v13, v13, v97, v97
	s_nop 1
	v_permlane32_swap_b32_e32 v207, v13
	v_max_f32_e32 v207, v207, v13
	v_mov_b32_e32 v13, v207
	s_nop 1
	v_permlane16_swap_b32_e32 v207, v13
	v_max_f32_e32 v207, v207, v13
	v_mov_b32_e32 v13, v207
	s_nop 1
	v_permlane32_swap_b32_e32 v207, v13
	v_add_f32_e32 v250, 0x41000000, v149
	v_cmp_gt_f32_e32 vcc, v207, v250
	s_cbranch_vccnz .Ldq0_p1_resc
	v_add_f32_e32 v250, 0x41000000, v159
	v_cmp_gt_f32_e32 vcc, v13, v250
	s_cbranch_vccz .Ldq0_p1_nores

.Ldq0_p1_nores:
	v_sub_f32_e32 v98, v98, v149
	v_exp_f32_e32 v98, v98
	v_sub_f32_e32 v99, v99, v149
	v_exp_f32_e32 v99, v99
	v_sub_f32_e32 v100, v100, v149
	v_exp_f32_e32 v100, v100
	v_sub_f32_e32 v101, v101, v149
	v_exp_f32_e32 v101, v101
	v_sub_f32_e32 v102, v102, v149
	v_exp_f32_e32 v102, v102
	v_sub_f32_e32 v103, v103, v149
	v_exp_f32_e32 v103, v103
	v_sub_f32_e32 v104, v104, v149
	v_exp_f32_e32 v104, v104
	v_sub_f32_e32 v105, v105, v149
	v_exp_f32_e32 v105, v105
	v_add_f32_e32 v12, v12, v98
	v_add_f32_e32 v12, v12, v99
	v_add_f32_e32 v12, v12, v100
	v_add_f32_e32 v12, v12, v101
	v_add_f32_e32 v12, v12, v102
	v_add_f32_e32 v12, v12, v103
	v_add_f32_e32 v12, v12, v104
	v_add_f32_e32 v12, v12, v105
	v_cvt_pk_bf16_f32 v98, v98, v99
	v_cvt_pk_bf16_f32 v99, v100, v101
	v_cvt_pk_bf16_f32 v100, v102, v103
	v_cvt_pk_bf16_f32 v101, v104, v105
	v_sub_f32_e32 v106, v106, v159
	v_exp_f32_e32 v106, v106
	v_sub_f32_e32 v107, v107, v159
	v_exp_f32_e32 v107, v107
	v_sub_f32_e32 v108, v108, v159
	v_exp_f32_e32 v108, v108
	v_sub_f32_e32 v109, v109, v159
	v_exp_f32_e32 v109, v109
	v_sub_f32_e32 v110, v110, v159
	v_exp_f32_e32 v110, v110
	v_sub_f32_e32 v111, v111, v159
	v_exp_f32_e32 v111, v111
	v_sub_f32_e32 v112, v112, v159
	v_exp_f32_e32 v112, v112
	v_sub_f32_e32 v113, v113, v159
	v_exp_f32_e32 v113, v113
	v_add_f32_e32 v157, v157, v106
	v_add_f32_e32 v157, v157, v107
	v_add_f32_e32 v157, v157, v108
	v_add_f32_e32 v157, v157, v109
	v_add_f32_e32 v157, v157, v110
	v_add_f32_e32 v157, v157, v111
	v_add_f32_e32 v157, v157, v112
	v_add_f32_e32 v157, v157, v113
	v_cvt_pk_bf16_f32 v106, v106, v107
	v_cvt_pk_bf16_f32 v107, v108, v109
	v_cvt_pk_bf16_f32 v108, v110, v111
	v_cvt_pk_bf16_f32 v109, v112, v113
	s_nop 1
	s_waitcnt lgkmcnt(4)
	v_mfma_f32_16x16x32_bf16 v[66:69], v[208:211], v[98:101], v[66:69]
	v_mfma_f32_16x16x32_bf16 v[70:73], v[208:211], v[106:109], v[70:73]
	ds_read_b128 v[208:211], v206 offset:55552
	v_sub_f32_e32 v82, v82, v149
	v_exp_f32_e32 v82, v82
	v_sub_f32_e32 v83, v83, v149
	v_exp_f32_e32 v83, v83
	v_sub_f32_e32 v84, v84, v149
	v_exp_f32_e32 v84, v84
	v_sub_f32_e32 v85, v85, v149
	v_exp_f32_e32 v85, v85
	s_waitcnt lgkmcnt(4)
	v_mfma_f32_16x16x32_bf16 v[74:77], v[252:255], v[98:101], v[74:77]
	v_mfma_f32_16x16x32_bf16 v[78:81], v[252:255], v[106:109], v[78:81]
	ds_read_b128 v[252:255], v206 offset:57856
	v_sub_f32_e32 v86, v86, v149
	v_exp_f32_e32 v86, v86
	v_sub_f32_e32 v87, v87, v149
	v_exp_f32_e32 v87, v87
	v_sub_f32_e32 v88, v88, v149
	v_exp_f32_e32 v88, v88
	v_sub_f32_e32 v89, v89, v149
	v_exp_f32_e32 v89, v89
	s_waitcnt lgkmcnt(4)
	v_mfma_f32_16x16x32_bf16 v[50:53], v[4:7], v[98:101], v[50:53]
	v_mfma_f32_16x16x32_bf16 v[54:57], v[4:7], v[106:109], v[54:57]
	ds_read_b128 v[4:7], v206 offset:60160
	v_add_f32_e32 v12, v12, v82
	v_add_f32_e32 v12, v12, v83
	v_add_f32_e32 v12, v12, v84
	v_add_f32_e32 v12, v12, v85
	v_add_f32_e32 v12, v12, v86
	v_add_f32_e32 v12, v12, v87
	v_add_f32_e32 v12, v12, v88
	v_add_f32_e32 v12, v12, v89
	s_waitcnt lgkmcnt(4)
	v_mfma_f32_16x16x32_bf16 v[58:61], v[8:11], v[98:101], v[58:61]
	v_mfma_f32_16x16x32_bf16 v[62:65], v[8:11], v[106:109], v[62:65]
	ds_read_b128 v[8:11], v206 offset:44096
	v_cvt_pk_bf16_f32 v82, v82, v83
	v_cvt_pk_bf16_f32 v83, v84, v85
	v_cvt_pk_bf16_f32 v84, v86, v87
	v_cvt_pk_bf16_f32 v85, v88, v89
	v_sub_f32_e32 v90, v90, v159
	v_exp_f32_e32 v90, v90
	v_sub_f32_e32 v91, v91, v159
	v_exp_f32_e32 v91, v91
	s_waitcnt lgkmcnt(4)
	v_mfma_f32_16x16x32_bf16 v[34:37], v[14:17], v[98:101], v[34:37]
	v_mfma_f32_16x16x32_bf16 v[38:41], v[14:17], v[106:109], v[38:41]
	ds_read_b128 v[14:17], v206 offset:46400
	v_sub_f32_e32 v92, v92, v159
	v_exp_f32_e32 v92, v92
	v_sub_f32_e32 v93, v93, v159
	v_exp_f32_e32 v93, v93
	v_sub_f32_e32 v94, v94, v159
	v_exp_f32_e32 v94, v94
	v_sub_f32_e32 v95, v95, v159
	v_exp_f32_e32 v95, v95
	s_waitcnt lgkmcnt(4)
	v_mfma_f32_16x16x32_bf16 v[42:45], v[208:211], v[98:101], v[42:45]
	v_mfma_f32_16x16x32_bf16 v[46:49], v[208:211], v[106:109], v[46:49]
	ds_read_b128 v[208:211], v206 offset:48704
	v_sub_f32_e32 v96, v96, v159
	v_exp_f32_e32 v96, v96
	v_sub_f32_e32 v97, v97, v159
	v_exp_f32_e32 v97, v97
	v_add_f32_e32 v157, v157, v90
	v_add_f32_e32 v157, v157, v91
	v_add_f32_e32 v157, v157, v92
	v_add_f32_e32 v157, v157, v93
	s_waitcnt lgkmcnt(4)
	v_mfma_f32_16x16x32_bf16 v[18:21], v[252:255], v[98:101], v[18:21]
	v_mfma_f32_16x16x32_bf16 v[22:25], v[252:255], v[106:109], v[22:25]
	ds_read_b128 v[252:255], v206 offset:51008
	v_add_f32_e32 v157, v157, v94
	v_add_f32_e32 v157, v157, v95
	v_add_f32_e32 v157, v157, v96
	v_add_f32_e32 v157, v157, v97
	v_cvt_pk_bf16_f32 v90, v90, v91
	v_cvt_pk_bf16_f32 v91, v92, v93
	v_cvt_pk_bf16_f32 v92, v94, v95
	v_cvt_pk_bf16_f32 v93, v96, v97
	s_waitcnt lgkmcnt(4)
	v_mfma_f32_16x16x32_bf16 v[26:29], v[4:7], v[98:101], v[26:29]
	v_mfma_f32_16x16x32_bf16 v[30:33], v[4:7], v[106:109], v[30:33]
	ds_read_b128 v[4:7], v206 offset:53312
	s_waitcnt lgkmcnt(4)
	v_mfma_f32_16x16x32_bf16 v[66:69], v[8:11], v[82:85], v[66:69]
	v_mfma_f32_16x16x32_bf16 v[70:73], v[8:11], v[90:93], v[70:73]
	ds_read_b128 v[8:11], v206 offset:55616
	s_waitcnt lgkmcnt(4)
	v_mfma_f32_16x16x32_bf16 v[74:77], v[14:17], v[82:85], v[74:77]
	v_mfma_f32_16x16x32_bf16 v[78:81], v[14:17], v[90:93], v[78:81]
	ds_read_b128 v[14:17], v206 offset:57920
	s_waitcnt lgkmcnt(4)
	v_mfma_f32_16x16x32_bf16 v[50:53], v[208:211], v[82:85], v[50:53]
	v_mfma_f32_16x16x32_bf16 v[54:57], v[208:211], v[90:93], v[54:57]
	ds_read_b128 v[208:211], v206 offset:60224
	s_waitcnt vmcnt(7)
	ds_write_b128 v167, v[212:215]
	s_waitcnt vmcnt(6)
	ds_write_b128 v169, v[216:219] offset:34816
	s_waitcnt lgkmcnt(6)
	v_mfma_f32_16x16x32_bf16 v[58:61], v[252:255], v[82:85], v[58:61]
	v_mfma_f32_16x16x32_bf16 v[62:65], v[252:255], v[90:93], v[62:65]
	s_waitcnt vmcnt(5)
	ds_write_b128 v182, v[220:223]
	s_waitcnt vmcnt(4)
	ds_write_b128 v185, v[224:227] offset:34816
	s_waitcnt lgkmcnt(7)
	v_mfma_f32_16x16x32_bf16 v[34:37], v[4:7], v[82:85], v[34:37]
	v_mfma_f32_16x16x32_bf16 v[38:41], v[4:7], v[90:93], v[38:41]
	s_waitcnt vmcnt(3)
	ds_write_b128 v187, v[228:231]
	s_waitcnt vmcnt(2)
	ds_write_b128 v190, v[232:235] offset:34816
	s_waitcnt lgkmcnt(8)
	v_mfma_f32_16x16x32_bf16 v[42:45], v[8:11], v[82:85], v[42:45]
	v_mfma_f32_16x16x32_bf16 v[46:49], v[8:11], v[90:93], v[46:49]
	s_waitcnt vmcnt(1)
	ds_write_b128 v170, v[236:239]
	s_waitcnt vmcnt(0)
	ds_write_b128 v172, v[240:243] offset:34816
	s_waitcnt lgkmcnt(9)
	v_mfma_f32_16x16x32_bf16 v[18:21], v[14:17], v[82:85], v[18:21]
	v_mfma_f32_16x16x32_bf16 v[22:25], v[14:17], v[90:93], v[22:25]
	s_waitcnt lgkmcnt(8)
	v_mfma_f32_16x16x32_bf16 v[26:29], v[208:211], v[82:85], v[26:29]
	v_mfma_f32_16x16x32_bf16 v[30:33], v[208:211], v[90:93], v[30:33]
	s_waitcnt lgkmcnt(0)
	s_barrier
	s_cmp_eq_u32 s38, s41
	s_cbranch_scc1 .Ldq0_exit
	s_mov_b32 s42, s41
	s_branch .Ldq0_p0_top
.Ldq0_exit:
	v_sub_u32_e32 v167, v167, v178
	v_lshrrev_b32_e32 v167, 1, v167
	v_sub_u32_e32 v182, v182, v178
	v_lshrrev_b32_e32 v182, 1, v182
	v_sub_u32_e32 v187, v187, v178
	v_lshrrev_b32_e32 v187, 1, v187
	v_sub_u32_e32 v170, v170, v178
	v_lshrrev_b32_e32 v170, 1, v170
	v_sub_u32_e32 v169, v169, v180
	v_sub_u32_e32 v185, v185, v180
	v_sub_u32_e32 v190, v190, v180
	v_sub_u32_e32 v172, v172, v180
	v_permlane16_swap_b32_e32 v66, v70
	v_permlane16_swap_b32_e32 v67, v71
	v_permlane16_swap_b32_e32 v68, v72
	v_permlane16_swap_b32_e32 v69, v73
	v_permlane16_swap_b32_e32 v74, v78
	v_permlane16_swap_b32_e32 v75, v79
	v_permlane16_swap_b32_e32 v76, v80
	v_permlane16_swap_b32_e32 v77, v81
	v_permlane16_swap_b32_e32 v50, v54
	v_permlane16_swap_b32_e32 v51, v55
	v_permlane16_swap_b32_e32 v52, v56
	v_permlane16_swap_b32_e32 v53, v57
	v_permlane16_swap_b32_e32 v58, v62
	v_permlane16_swap_b32_e32 v59, v63
	v_permlane16_swap_b32_e32 v60, v64
	v_permlane16_swap_b32_e32 v61, v65
	v_permlane16_swap_b32_e32 v34, v38
	v_permlane16_swap_b32_e32 v35, v39
	v_permlane16_swap_b32_e32 v36, v40
	v_permlane16_swap_b32_e32 v37, v41
	v_permlane16_swap_b32_e32 v42, v46
	v_permlane16_swap_b32_e32 v43, v47
	v_permlane16_swap_b32_e32 v44, v48
	v_permlane16_swap_b32_e32 v45, v49
	v_permlane16_swap_b32_e32 v18, v22
	v_permlane16_swap_b32_e32 v19, v23
	v_permlane16_swap_b32_e32 v20, v24
	v_permlane16_swap_b32_e32 v21, v25
	v_permlane16_swap_b32_e32 v26, v30
	v_permlane16_swap_b32_e32 v27, v31
	v_permlane16_swap_b32_e32 v28, v32
	v_permlane16_swap_b32_e32 v29, v33
	v_permlane32_swap_b32_e32 v66, v70
	v_permlane32_swap_b32_e32 v67, v71
	v_permlane32_swap_b32_e32 v68, v72
	v_permlane32_swap_b32_e32 v69, v73
	v_permlane32_swap_b32_e32 v74, v78
	v_permlane32_swap_b32_e32 v75, v79
	v_permlane32_swap_b32_e32 v76, v80
	v_permlane32_swap_b32_e32 v77, v81
	v_permlane32_swap_b32_e32 v50, v54
	v_permlane32_swap_b32_e32 v51, v55
	v_permlane32_swap_b32_e32 v52, v56
	v_permlane32_swap_b32_e32 v53, v57
	v_permlane32_swap_b32_e32 v58, v62
	v_permlane32_swap_b32_e32 v59, v63
	v_permlane32_swap_b32_e32 v60, v64
	v_permlane32_swap_b32_e32 v61, v65
	v_permlane32_swap_b32_e32 v34, v38
	v_permlane32_swap_b32_e32 v35, v39
	v_permlane32_swap_b32_e32 v36, v40
	v_permlane32_swap_b32_e32 v37, v41
	v_permlane32_swap_b32_e32 v42, v46
	v_permlane32_swap_b32_e32 v43, v47
	v_permlane32_swap_b32_e32 v44, v48
	v_permlane32_swap_b32_e32 v45, v49
	v_permlane32_swap_b32_e32 v18, v22
	v_permlane32_swap_b32_e32 v19, v23
	v_permlane32_swap_b32_e32 v20, v24
	v_permlane32_swap_b32_e32 v21, v25
	v_permlane32_swap_b32_e32 v26, v30
	v_permlane32_swap_b32_e32 v27, v31
	v_permlane32_swap_b32_e32 v28, v32
	v_permlane32_swap_b32_e32 v29, v33
	v_permlane32_swap_b32_e32 v12, v157
	v_add_f32_e32 v12, v12, v157
	v_mov_b32_e32 v157, v12
	s_nop 1
	v_permlane16_swap_b32_e32 v12, v157
	v_add_f32_e32 v12, v12, v157
	v_mov_b32_e32 v157, v12
	s_nop 1
	v_permlane32_swap_b32_e32 v12, v157
	v_and_b32_e32 v250, 16, v1
	v_cmp_ne_u32_e32 vcc, 0, v250
	v_cndmask_b32_e32 v12, v12, v157, vcc
	v_cndmask_b32_e32 v149, v149, v159, vcc
	v_and_b32_e32 v13, 32, v1
	v_cmp_eq_u32_e64 s[0:1], 0, v13
	v_cndmask_b32_e64 v12, 0, v12, s[0:1]
	v_and_b32_e32 v250, 15, v1
	v_bfe_u32 v13, v1, 5, 1
	v_lshl_add_u32 v250, v13, 4, v250
	v_lshlrev_b32_e32 v250, 2, v250
	v_add_u32_e32 v13, 0x80, v250
	ds_bpermute_b32 v4, v250, v126
	ds_bpermute_b32 v5, v250, v122
	ds_bpermute_b32 v6, v13, v126
	ds_bpermute_b32 v7, v13, v122
	s_waitcnt lgkmcnt(0)
	v_cndmask_b32_e32 v126, v4, v5, vcc
	v_cndmask_b32_e32 v122, v6, v7, vcc
	ds_bpermute_b32 v4, v250, v127
	ds_bpermute_b32 v5, v250, v123
	ds_bpermute_b32 v6, v13, v127
	ds_bpermute_b32 v7, v13, v123
	s_waitcnt lgkmcnt(0)
	v_cndmask_b32_e32 v127, v4, v5, vcc
	v_cndmask_b32_e32 v123, v6, v7, vcc
	ds_bpermute_b32 v4, v250, v128
	ds_bpermute_b32 v5, v250, v124
	ds_bpermute_b32 v6, v13, v128
	ds_bpermute_b32 v7, v13, v124
	s_waitcnt lgkmcnt(0)
	v_cndmask_b32_e32 v128, v4, v5, vcc
	v_cndmask_b32_e32 v124, v6, v7, vcc
	ds_bpermute_b32 v4, v250, v129
	ds_bpermute_b32 v5, v250, v125
	ds_bpermute_b32 v6, v13, v129
	ds_bpermute_b32 v7, v13, v125
	s_waitcnt lgkmcnt(0)
	v_cndmask_b32_e32 v129, v4, v5, vcc
	v_cndmask_b32_e32 v125, v6, v7, vcc
	ds_bpermute_b32 v4, v250, v118
	ds_bpermute_b32 v5, v250, v114
	ds_bpermute_b32 v6, v13, v118
	ds_bpermute_b32 v7, v13, v114
	s_waitcnt lgkmcnt(0)
	v_cndmask_b32_e32 v118, v4, v5, vcc
	v_cndmask_b32_e32 v114, v6, v7, vcc
	ds_bpermute_b32 v4, v250, v119
	ds_bpermute_b32 v5, v250, v115
	ds_bpermute_b32 v6, v13, v119
	ds_bpermute_b32 v7, v13, v115
	s_waitcnt lgkmcnt(0)
	v_cndmask_b32_e32 v119, v4, v5, vcc
	v_cndmask_b32_e32 v115, v6, v7, vcc
	ds_bpermute_b32 v4, v250, v120
	ds_bpermute_b32 v5, v250, v116
	ds_bpermute_b32 v6, v13, v120
	ds_bpermute_b32 v7, v13, v116
	s_waitcnt lgkmcnt(0)
	v_cndmask_b32_e32 v120, v4, v5, vcc
	v_cndmask_b32_e32 v116, v6, v7, vcc
	ds_bpermute_b32 v4, v250, v121
	ds_bpermute_b32 v5, v250, v117
	ds_bpermute_b32 v6, v13, v121
	ds_bpermute_b32 v7, v13, v117
	s_waitcnt lgkmcnt(0)
	v_cndmask_b32_e32 v121, v4, v5, vcc
	v_cndmask_b32_e32 v117, v6, v7, vcc

.LBB0_1447:
	v_lshlrev_b32_e32 v2, 1, v2
	v_lshlrev_b32_e32 v162, 1, v162
	v_lshlrev_b32_e32 v160, 1, v160
	v_lshlrev_b32_e32 v158, 1, v158
	v_lshlrev_b32_e32 v244, 1, v10
	v_lshlrev_b32_e32 v245, 1, v8
	v_lshlrev_b32_e32 v246, 1, v6
	v_lshlrev_b32_e32 v249, 1, v4
	v_mov_b32_e32 v159, 0
	v_mov_b32_e32 v161, v151
	v_lshl_add_u32 v168, v168, 1, v179
	v_lshl_add_u32 v183, v183, 1, v179
	v_lshl_add_u32 v190, v190, 1, v179
	v_lshl_add_u32 v171, v171, 1, v179
	v_add_u32_e32 v170, v170, v181
	v_add_u32_e32 v188, v188, v181
	v_add_u32_e32 v193, v193, v181
	v_add_u32_e32 v173, v173, v181
	v_bfe_u32 v250, v1, 4, 2
	v_lshrrev_b32_e32 v13, 1, v250
	v_sub_u32_e32 v13, v250, v13
	v_lshlrev_b32_e32 v13, 4, v13
	v_and_b32_e32 v250, 1, v250
	v_mul_u32_u24_e32 v251, 0x900, v250
	v_sub_u32_e32 v163, v13, v251
	v_add_u32_e32 v163, v163, v175
	v_add_u32_e32 v163, 0x2400, v163
	v_bfe_u32 v251, v1, 3, 1
	v_lshlrev_b32_e32 v251, 3, v251
	v_lshlrev_b32_e32 v250, 4, v250
	v_sub_u32_e32 v251, v251, v250
	v_mul_i32_i24_e32 v251, 0x110, v251
	v_add3_u32 v207, v251, v13, v174
	s_waitcnt vmcnt(0)
	v_and_b32_e32 v250, 15, v1
	v_bfe_u32 v13, v1, 4, 1
	v_lshl_add_u32 v250, v13, 5, v250
	v_lshlrev_b32_e32 v250, 2, v250
	v_add_u32_e32 v13, 64, v250
	v_and_b32_e32 v251, 32, v1
	v_cmp_ne_u32_e32 vcc, 0, v251
	ds_bpermute_b32 v4, v250, v126
	ds_bpermute_b32 v5, v250, v122
	ds_bpermute_b32 v6, v13, v126
	ds_bpermute_b32 v7, v13, v122
	s_waitcnt lgkmcnt(0)
	v_cndmask_b32_e32 v126, v4, v5, vcc
	v_cndmask_b32_e32 v122, v6, v7, vcc
	ds_bpermute_b32 v4, v250, v127
	ds_bpermute_b32 v5, v250, v123
	ds_bpermute_b32 v6, v13, v127
	ds_bpermute_b32 v7, v13, v123
	s_waitcnt lgkmcnt(0)
	v_cndmask_b32_e32 v127, v4, v5, vcc
	v_cndmask_b32_e32 v123, v6, v7, vcc
	ds_bpermute_b32 v4, v250, v128
	ds_bpermute_b32 v5, v250, v124
	ds_bpermute_b32 v6, v13, v128
	ds_bpermute_b32 v7, v13, v124
	s_waitcnt lgkmcnt(0)
	v_cndmask_b32_e32 v128, v4, v5, vcc
	v_cndmask_b32_e32 v124, v6, v7, vcc
	ds_bpermute_b32 v4, v250, v129
	ds_bpermute_b32 v5, v250, v125
	ds_bpermute_b32 v6, v13, v129
	ds_bpermute_b32 v7, v13, v125
	s_waitcnt lgkmcnt(0)
	v_cndmask_b32_e32 v129, v4, v5, vcc
	v_cndmask_b32_e32 v125, v6, v7, vcc
	ds_bpermute_b32 v4, v250, v118
	ds_bpermute_b32 v5, v250, v114
	ds_bpermute_b32 v6, v13, v118
	ds_bpermute_b32 v7, v13, v114
	s_waitcnt lgkmcnt(0)
	v_cndmask_b32_e32 v118, v4, v5, vcc
	v_cndmask_b32_e32 v114, v6, v7, vcc
	ds_bpermute_b32 v4, v250, v119
	ds_bpermute_b32 v5, v250, v115
	ds_bpermute_b32 v6, v13, v119
	ds_bpermute_b32 v7, v13, v115
	s_waitcnt lgkmcnt(0)
	v_cndmask_b32_e32 v119, v4, v5, vcc
	v_cndmask_b32_e32 v115, v6, v7, vcc
	ds_bpermute_b32 v4, v250, v120
	ds_bpermute_b32 v5, v250, v116
	ds_bpermute_b32 v6, v13, v120
	ds_bpermute_b32 v7, v13, v116
	s_waitcnt lgkmcnt(0)
	v_cndmask_b32_e32 v120, v4, v5, vcc
	v_cndmask_b32_e32 v116, v6, v7, vcc
	ds_bpermute_b32 v4, v250, v121
	ds_bpermute_b32 v5, v250, v117
	ds_bpermute_b32 v6, v13, v121
	ds_bpermute_b32 v7, v13, v117
	s_waitcnt lgkmcnt(0)
	v_cndmask_b32_e32 v121, v4, v5, vcc
	v_cndmask_b32_e32 v117, v6, v7, vcc

.Ldq1_p0_addr:
	global_load_dwordx4 v[212:215], v2, s[24:25]
	global_load_dwordx4 v[216:219], v244, s[20:21]
	global_load_dwordx4 v[220:223], v162, s[24:25]
	global_load_dwordx4 v[224:227], v245, s[20:21]
	global_load_dwordx4 v[228:231], v160, s[24:25]
	global_load_dwordx4 v[232:235], v246, s[20:21]
	global_load_dwordx4 v[236:239], v158, s[24:25]
	global_load_dwordx4 v[240:243], v249, s[20:21]
	ds_read_b128 v[4:7], v207
	ds_read_b128 v[8:11], v207 offset:2176
	ds_read_b128 v[14:17], v207 offset:8704
	ds_read_b128 v[208:211], v207 offset:10880
	ds_read_b128 v[252:255], v207 offset:64
	s_waitcnt vmcnt(8)
	s_waitcnt lgkmcnt(4)
	v_mfma_f32_16x16x32_bf16 v[98:101], v[4:7], v[126:129], 0
	v_mfma_f32_16x16x32_bf16 v[106:109], v[4:7], v[122:125], 0
	ds_read_b128 v[4:7], v207 offset:2240
	s_waitcnt lgkmcnt(4)
	v_mfma_f32_16x16x32_bf16 v[102:105], v[8:11], v[126:129], 0
	v_mfma_f32_16x16x32_bf16 v[110:113], v[8:11], v[122:125], 0
	ds_read_b128 v[8:11], v207 offset:8768
	s_waitcnt lgkmcnt(4)
	v_mfma_f32_16x16x32_bf16 v[82:85], v[14:17], v[126:129], 0
	v_mfma_f32_16x16x32_bf16 v[90:93], v[14:17], v[122:125], 0
	ds_read_b128 v[14:17], v207 offset:10944
	s_waitcnt lgkmcnt(4)
	v_mfma_f32_16x16x32_bf16 v[86:89], v[208:211], v[126:129], 0
	v_mfma_f32_16x16x32_bf16 v[94:97], v[208:211], v[122:125], 0
	ds_read_b128 v[208:211], v163 offset:25600
	s_waitcnt lgkmcnt(4)
	v_mfma_f32_16x16x32_bf16 v[98:101], v[252:255], v[118:121], v[98:101]
	v_mfma_f32_16x16x32_bf16 v[106:109], v[252:255], v[114:117], v[106:109]
	ds_read_b128 v[252:255], v163 offset:27904
	s_waitcnt lgkmcnt(4)
	v_mfma_f32_16x16x32_bf16 v[102:105], v[4:7], v[118:121], v[102:105]
	v_mfma_f32_16x16x32_bf16 v[110:113], v[4:7], v[114:117], v[110:113]
	ds_read_b128 v[4:7], v163 offset:30208
	s_waitcnt lgkmcnt(4)
	v_mfma_f32_16x16x32_bf16 v[82:85], v[8:11], v[118:121], v[82:85]
	v_mfma_f32_16x16x32_bf16 v[90:93], v[8:11], v[114:117], v[90:93]
	ds_read_b128 v[8:11], v163 offset:32512
	s_waitcnt lgkmcnt(4)
	v_mfma_f32_16x16x32_bf16 v[86:89], v[14:17], v[118:121], v[86:89]
	v_mfma_f32_16x16x32_bf16 v[94:97], v[14:17], v[114:117], v[94:97]
	ds_read_b128 v[14:17], v163 offset:34816
	s_nop 7
	s_nop 1
	v_max3_f32 v251, v98, v99, v100
	v_max3_f32 v251, v251, v101, v102
	v_max3_f32 v251, v251, v103, v104
	v_max3_f32 v251, v251, v105, v82
	v_max3_f32 v251, v251, v83, v84
	v_max3_f32 v251, v251, v85, v86
	v_max3_f32 v251, v251, v87, v88
	v_max3_f32 v251, v251, v89, v89
	v_max3_f32 v13, v106, v107, v108
	v_max3_f32 v13, v13, v109, v110
	v_max3_f32 v13, v13, v111, v112
	v_max3_f32 v13, v13, v113, v90
	v_max3_f32 v13, v13, v91, v92
	v_max3_f32 v13, v13, v93, v94
	v_max3_f32 v13, v13, v95, v96
	v_max3_f32 v13, v13, v97, v97
	s_nop 1
	v_permlane32_swap_b32_e32 v251, v13
	v_max_f32_e32 v251, v251, v13
	v_mov_b32_e32 v13, v251
	s_nop 1
	v_permlane16_swap_b32_e32 v251, v13
	v_max_f32_e32 v251, v251, v13
	v_mov_b32_e32 v13, v251
	s_nop 1
	v_permlane32_swap_b32_e32 v251, v13
	v_add_f32_e32 v250, 0x41000000, v151
	v_cmp_gt_f32_e32 vcc, v251, v250
	s_cbranch_vccnz .Ldq1_p0_resc
	v_add_f32_e32 v250, 0x41000000, v161
	v_cmp_gt_f32_e32 vcc, v13, v250
	s_cbranch_vccz .Ldq1_p0_nores
.Ldq1_p0_resc:
	v_max_f32_e32 v251, v151, v251
	v_sub_f32_e32 v250, v151, v251
	v_exp_f32_e32 v250, v250
	v_mov_b32_e32 v151, v251
	v_pk_mul_f32 v[66:67], v[66:67], v[250:251] op_sel_hi:[1,0]
	v_pk_mul_f32 v[68:69], v[68:69], v[250:251] op_sel_hi:[1,0]
	v_pk_mul_f32 v[74:75], v[74:75], v[250:251] op_sel_hi:[1,0]
	v_pk_mul_f32 v[76:77], v[76:77], v[250:251] op_sel_hi:[1,0]
	v_pk_mul_f32 v[50:51], v[50:51], v[250:251] op_sel_hi:[1,0]
	v_pk_mul_f32 v[52:53], v[52:53], v[250:251] op_sel_hi:[1,0]
	v_pk_mul_f32 v[58:59], v[58:59], v[250:251] op_sel_hi:[1,0]
	v_pk_mul_f32 v[60:61], v[60:61], v[250:251] op_sel_hi:[1,0]
	v_pk_mul_f32 v[34:35], v[34:35], v[250:251] op_sel_hi:[1,0]
	v_pk_mul_f32 v[36:37], v[36:37], v[250:251] op_sel_hi:[1,0]
	v_pk_mul_f32 v[42:43], v[42:43], v[250:251] op_sel_hi:[1,0]
	v_pk_mul_f32 v[44:45], v[44:45], v[250:251] op_sel_hi:[1,0]
	v_pk_mul_f32 v[18:19], v[18:19], v[250:251] op_sel_hi:[1,0]
	v_pk_mul_f32 v[20:21], v[20:21], v[250:251] op_sel_hi:[1,0]
	v_pk_mul_f32 v[26:27], v[26:27], v[250:251] op_sel_hi:[1,0]
	v_pk_mul_f32 v[28:29], v[28:29], v[250:251] op_sel_hi:[1,0]
	v_mul_f32_e32 v12, v12, v250
	v_max_f32_e32 v13, v161, v13
	v_sub_f32_e32 v250, v161, v13
	v_exp_f32_e32 v250, v250
	v_mov_b32_e32 v161, v13
	v_pk_mul_f32 v[70:71], v[70:71], v[250:251] op_sel_hi:[1,0]
	v_pk_mul_f32 v[72:73], v[72:73], v[250:251] op_sel_hi:[1,0]
	v_pk_mul_f32 v[78:79], v[78:79], v[250:251] op_sel_hi:[1,0]
	v_pk_mul_f32 v[80:81], v[80:81], v[250:251] op_sel_hi:[1,0]
	v_pk_mul_f32 v[54:55], v[54:55], v[250:251] op_sel_hi:[1,0]
	v_pk_mul_f32 v[56:57], v[56:57], v[250:251] op_sel_hi:[1,0]
	v_pk_mul_f32 v[62:63], v[62:63], v[250:251] op_sel_hi:[1,0]
	v_pk_mul_f32 v[64:65], v[64:65], v[250:251] op_sel_hi:[1,0]
	v_pk_mul_f32 v[38:39], v[38:39], v[250:251] op_sel_hi:[1,0]
	v_pk_mul_f32 v[40:41], v[40:41], v[250:251] op_sel_hi:[1,0]
	v_pk_mul_f32 v[46:47], v[46:47], v[250:251] op_sel_hi:[1,0]
	v_pk_mul_f32 v[48:49], v[48:49], v[250:251] op_sel_hi:[1,0]
	v_pk_mul_f32 v[22:23], v[22:23], v[250:251] op_sel_hi:[1,0]
	v_pk_mul_f32 v[24:25], v[24:25], v[250:251] op_sel_hi:[1,0]
	v_pk_mul_f32 v[30:31], v[30:31], v[250:251] op_sel_hi:[1,0]
	v_pk_mul_f32 v[32:33], v[32:33], v[250:251] op_sel_hi:[1,0]
	v_mul_f32_e32 v159, v159, v250
.Ldq1_p0_nores:
	v_sub_f32_e32 v98, v98, v151
	v_exp_f32_e32 v98, v98
	v_sub_f32_e32 v99, v99, v151
	v_exp_f32_e32 v99, v99
	v_sub_f32_e32 v100, v100, v151
	v_exp_f32_e32 v100, v100
	v_sub_f32_e32 v101, v101, v151
	v_exp_f32_e32 v101, v101
	v_sub_f32_e32 v102, v102, v151
	v_exp_f32_e32 v102, v102
	v_sub_f32_e32 v103, v103, v151
	v_exp_f32_e32 v103, v103
	v_sub_f32_e32 v104, v104, v151
	v_exp_f32_e32 v104, v104
	v_sub_f32_e32 v105, v105, v151
	v_exp_f32_e32 v105, v105
	v_add_f32_e32 v12, v12, v98
	v_add_f32_e32 v12, v12, v99
	v_add_f32_e32 v12, v12, v100
	v_add_f32_e32 v12, v12, v101
	v_add_f32_e32 v12, v12, v102
	v_add_f32_e32 v12, v12, v103
	v_add_f32_e32 v12, v12, v104
	v_add_f32_e32 v12, v12, v105
	v_cvt_pk_bf16_f32 v98, v98, v99
	v_cvt_pk_bf16_f32 v99, v100, v101
	v_cvt_pk_bf16_f32 v100, v102, v103
	v_cvt_pk_bf16_f32 v101, v104, v105
	v_sub_f32_e32 v106, v106, v161
	v_exp_f32_e32 v106, v106
	v_sub_f32_e32 v107, v107, v161
	v_exp_f32_e32 v107, v107
	v_sub_f32_e32 v108, v108, v161
	v_exp_f32_e32 v108, v108
	v_sub_f32_e32 v109, v109, v161
	v_exp_f32_e32 v109, v109
	v_sub_f32_e32 v110, v110, v161
	v_exp_f32_e32 v110, v110
	v_sub_f32_e32 v111, v111, v161
	v_exp_f32_e32 v111, v111
	v_sub_f32_e32 v112, v112, v161
	v_exp_f32_e32 v112, v112
	v_sub_f32_e32 v113, v113, v161
	v_exp_f32_e32 v113, v113
	v_add_f32_e32 v159, v159, v106
	v_add_f32_e32 v159, v159, v107
	v_add_f32_e32 v159, v159, v108
	v_add_f32_e32 v159, v159, v109
	v_add_f32_e32 v159, v159, v110
	v_add_f32_e32 v159, v159, v111
	v_add_f32_e32 v159, v159, v112
	v_add_f32_e32 v159, v159, v113
	v_cvt_pk_bf16_f32 v106, v106, v107
	v_cvt_pk_bf16_f32 v107, v108, v109
	v_cvt_pk_bf16_f32 v108, v110, v111
	v_cvt_pk_bf16_f32 v109, v112, v113
	s_nop 1
	s_waitcnt lgkmcnt(4)
	v_mfma_f32_16x16x32_bf16 v[66:69], v[208:211], v[98:101], v[66:69]
	v_mfma_f32_16x16x32_bf16 v[70:73], v[208:211], v[106:109], v[70:73]
	ds_read_b128 v[208:211], v163 offset:37120
	v_sub_f32_e32 v82, v82, v151
	v_exp_f32_e32 v82, v82
	v_sub_f32_e32 v83, v83, v151
	v_exp_f32_e32 v83, v83
	v_sub_f32_e32 v84, v84, v151
	v_exp_f32_e32 v84, v84
	v_sub_f32_e32 v85, v85, v151
	v_exp_f32_e32 v85, v85
	s_waitcnt lgkmcnt(4)
	v_mfma_f32_16x16x32_bf16 v[74:77], v[252:255], v[98:101], v[74:77]
	v_mfma_f32_16x16x32_bf16 v[78:81], v[252:255], v[106:109], v[78:81]
	ds_read_b128 v[252:255], v163 offset:39424
	v_sub_f32_e32 v86, v86, v151
	v_exp_f32_e32 v86, v86
	v_sub_f32_e32 v87, v87, v151
	v_exp_f32_e32 v87, v87
	v_sub_f32_e32 v88, v88, v151
	v_exp_f32_e32 v88, v88
	v_sub_f32_e32 v89, v89, v151
	v_exp_f32_e32 v89, v89
	s_waitcnt lgkmcnt(4)
	v_mfma_f32_16x16x32_bf16 v[50:53], v[4:7], v[98:101], v[50:53]
	v_mfma_f32_16x16x32_bf16 v[54:57], v[4:7], v[106:109], v[54:57]
	ds_read_b128 v[4:7], v163 offset:41728
	v_add_f32_e32 v12, v12, v82
	v_add_f32_e32 v12, v12, v83
	v_add_f32_e32 v12, v12, v84
	v_add_f32_e32 v12, v12, v85
	v_add_f32_e32 v12, v12, v86
	v_add_f32_e32 v12, v12, v87
	v_add_f32_e32 v12, v12, v88
	v_add_f32_e32 v12, v12, v89
	s_waitcnt lgkmcnt(4)
	v_mfma_f32_16x16x32_bf16 v[58:61], v[8:11], v[98:101], v[58:61]
	v_mfma_f32_16x16x32_bf16 v[62:65], v[8:11], v[106:109], v[62:65]
	ds_read_b128 v[8:11], v163 offset:25664
	v_cvt_pk_bf16_f32 v82, v82, v83
	v_cvt_pk_bf16_f32 v83, v84, v85
	v_cvt_pk_bf16_f32 v84, v86, v87
	v_cvt_pk_bf16_f32 v85, v88, v89
	v_sub_f32_e32 v90, v90, v161
	v_exp_f32_e32 v90, v90
	v_sub_f32_e32 v91, v91, v161
	v_exp_f32_e32 v91, v91
	s_waitcnt lgkmcnt(4)
	v_mfma_f32_16x16x32_bf16 v[34:37], v[14:17], v[98:101], v[34:37]
	v_mfma_f32_16x16x32_bf16 v[38:41], v[14:17], v[106:109], v[38:41]
	ds_read_b128 v[14:17], v163 offset:27968
	v_sub_f32_e32 v92, v92, v161
	v_exp_f32_e32 v92, v92
	v_sub_f32_e32 v93, v93, v161
	v_exp_f32_e32 v93, v93
	v_sub_f32_e32 v94, v94, v161
	v_exp_f32_e32 v94, v94
	v_sub_f32_e32 v95, v95, v161
	v_exp_f32_e32 v95, v95
	s_waitcnt lgkmcnt(4)
	v_mfma_f32_16x16x32_bf16 v[42:45], v[208:211], v[98:101], v[42:45]
	v_mfma_f32_16x16x32_bf16 v[46:49], v[208:211], v[106:109], v[46:49]
	ds_read_b128 v[208:211], v163 offset:30272
	v_sub_f32_e32 v96, v96, v161
	v_exp_f32_e32 v96, v96
	v_sub_f32_e32 v97, v97, v161
	v_exp_f32_e32 v97, v97
	v_add_f32_e32 v159, v159, v90
	v_add_f32_e32 v159, v159, v91
	v_add_f32_e32 v159, v159, v92
	v_add_f32_e32 v159, v159, v93
	s_waitcnt lgkmcnt(4)
	v_mfma_f32_16x16x32_bf16 v[18:21], v[252:255], v[98:101], v[18:21]
	v_mfma_f32_16x16x32_bf16 v[22:25], v[252:255], v[106:109], v[22:25]
	ds_read_b128 v[252:255], v163 offset:32576
	v_add_f32_e32 v159, v159, v94
	v_add_f32_e32 v159, v159, v95
	v_add_f32_e32 v159, v159, v96
	v_add_f32_e32 v159, v159, v97
	v_cvt_pk_bf16_f32 v90, v90, v91
	v_cvt_pk_bf16_f32 v91, v92, v93
	v_cvt_pk_bf16_f32 v92, v94, v95
	v_cvt_pk_bf16_f32 v93, v96, v97
	s_waitcnt lgkmcnt(4)
	v_mfma_f32_16x16x32_bf16 v[26:29], v[4:7], v[98:101], v[26:29]
	v_mfma_f32_16x16x32_bf16 v[30:33], v[4:7], v[106:109], v[30:33]
	ds_read_b128 v[4:7], v163 offset:34880
	s_waitcnt lgkmcnt(4)
	v_mfma_f32_16x16x32_bf16 v[66:69], v[8:11], v[82:85], v[66:69]
	v_mfma_f32_16x16x32_bf16 v[70:73], v[8:11], v[90:93], v[70:73]
	ds_read_b128 v[8:11], v163 offset:37184
	s_waitcnt lgkmcnt(4)
	v_mfma_f32_16x16x32_bf16 v[74:77], v[14:17], v[82:85], v[74:77]
	v_mfma_f32_16x16x32_bf16 v[78:81], v[14:17], v[90:93], v[78:81]
	ds_read_b128 v[14:17], v163 offset:39488
	s_waitcnt lgkmcnt(4)
	v_mfma_f32_16x16x32_bf16 v[50:53], v[208:211], v[82:85], v[50:53]
	v_mfma_f32_16x16x32_bf16 v[54:57], v[208:211], v[90:93], v[54:57]
	ds_read_b128 v[208:211], v163 offset:41792
	s_waitcnt vmcnt(7)
	ds_write_b128 v168, v[212:215] offset:17408
	s_waitcnt vmcnt(6)
	ds_write_b128 v170, v[216:219] offset:53248
	s_waitcnt lgkmcnt(6)
	v_mfma_f32_16x16x32_bf16 v[58:61], v[252:255], v[82:85], v[58:61]
	v_mfma_f32_16x16x32_bf16 v[62:65], v[252:255], v[90:93], v[62:65]
	s_waitcnt vmcnt(5)
	ds_write_b128 v183, v[220:223] offset:17408
	s_waitcnt vmcnt(4)
	ds_write_b128 v188, v[224:227] offset:53248
	s_waitcnt lgkmcnt(7)
	v_mfma_f32_16x16x32_bf16 v[34:37], v[4:7], v[82:85], v[34:37]
	v_mfma_f32_16x16x32_bf16 v[38:41], v[4:7], v[90:93], v[38:41]
	s_waitcnt vmcnt(3)
	ds_write_b128 v190, v[228:231] offset:17408
	s_waitcnt vmcnt(2)
	ds_write_b128 v193, v[232:235] offset:53248
	s_waitcnt lgkmcnt(8)
	v_mfma_f32_16x16x32_bf16 v[42:45], v[8:11], v[82:85], v[42:45]
	v_mfma_f32_16x16x32_bf16 v[46:49], v[8:11], v[90:93], v[46:49]
	s_waitcnt vmcnt(1)
	ds_write_b128 v171, v[236:239] offset:17408
	s_waitcnt vmcnt(0)
	ds_write_b128 v173, v[240:243] offset:53248
	s_waitcnt lgkmcnt(9)
	v_mfma_f32_16x16x32_bf16 v[18:21], v[14:17], v[82:85], v[18:21]
	v_mfma_f32_16x16x32_bf16 v[22:25], v[14:17], v[90:93], v[22:25]
	s_waitcnt lgkmcnt(8)
	v_mfma_f32_16x16x32_bf16 v[26:29], v[208:211], v[82:85], v[26:29]
	v_mfma_f32_16x16x32_bf16 v[30:33], v[208:211], v[90:93], v[30:33]
	s_waitcnt lgkmcnt(0)
	s_barrier
	s_cmp_eq_u32 s38, s41
	s_cbranch_scc1 .Ldq1_exit
	s_mov_b32 s42, s41

.Ldq1_p1_addr:
	global_load_dwordx4 v[212:215], v2, s[24:25]
	global_load_dwordx4 v[216:219], v244, s[20:21]
	global_load_dwordx4 v[220:223], v162, s[24:25]
	global_load_dwordx4 v[224:227], v245, s[20:21]
	global_load_dwordx4 v[228:231], v160, s[24:25]
	global_load_dwordx4 v[232:235], v246, s[20:21]
	global_load_dwordx4 v[236:239], v158, s[24:25]
	global_load_dwordx4 v[240:243], v249, s[20:21]
	ds_read_b128 v[4:7], v207 offset:17408
	ds_read_b128 v[8:11], v207 offset:19584
	ds_read_b128 v[14:17], v207 offset:26112
	ds_read_b128 v[208:211], v207 offset:28288
	ds_read_b128 v[252:255], v207 offset:17472
	s_waitcnt vmcnt(8)
	s_waitcnt lgkmcnt(4)
	v_mfma_f32_16x16x32_bf16 v[98:101], v[4:7], v[126:129], 0
	v_mfma_f32_16x16x32_bf16 v[106:109], v[4:7], v[122:125], 0
	ds_read_b128 v[4:7], v207 offset:19648
	s_waitcnt lgkmcnt(4)
	v_mfma_f32_16x16x32_bf16 v[102:105], v[8:11], v[126:129], 0
	v_mfma_f32_16x16x32_bf16 v[110:113], v[8:11], v[122:125], 0
	ds_read_b128 v[8:11], v207 offset:26176
	s_waitcnt lgkmcnt(4)
	v_mfma_f32_16x16x32_bf16 v[82:85], v[14:17], v[126:129], 0
	v_mfma_f32_16x16x32_bf16 v[90:93], v[14:17], v[122:125], 0
	ds_read_b128 v[14:17], v207 offset:28352
	s_waitcnt lgkmcnt(4)
	v_mfma_f32_16x16x32_bf16 v[86:89], v[208:211], v[126:129], 0
	v_mfma_f32_16x16x32_bf16 v[94:97], v[208:211], v[122:125], 0
	ds_read_b128 v[208:211], v163 offset:44032
	s_waitcnt lgkmcnt(4)
	v_mfma_f32_16x16x32_bf16 v[98:101], v[252:255], v[118:121], v[98:101]
	v_mfma_f32_16x16x32_bf16 v[106:109], v[252:255], v[114:117], v[106:109]
	ds_read_b128 v[252:255], v163 offset:46336
	s_waitcnt lgkmcnt(4)
	v_mfma_f32_16x16x32_bf16 v[102:105], v[4:7], v[118:121], v[102:105]
	v_mfma_f32_16x16x32_bf16 v[110:113], v[4:7], v[114:117], v[110:113]
	ds_read_b128 v[4:7], v163 offset:48640
	s_waitcnt lgkmcnt(4)
	v_mfma_f32_16x16x32_bf16 v[82:85], v[8:11], v[118:121], v[82:85]
	v_mfma_f32_16x16x32_bf16 v[90:93], v[8:11], v[114:117], v[90:93]
	ds_read_b128 v[8:11], v163 offset:50944
	s_waitcnt lgkmcnt(4)
	v_mfma_f32_16x16x32_bf16 v[86:89], v[14:17], v[118:121], v[86:89]
	v_mfma_f32_16x16x32_bf16 v[94:97], v[14:17], v[114:117], v[94:97]
	ds_read_b128 v[14:17], v163 offset:53248
	s_nop 7
	s_nop 1
	v_max3_f32 v251, v98, v99, v100
	v_max3_f32 v251, v251, v101, v102
	v_max3_f32 v251, v251, v103, v104
	v_max3_f32 v251, v251, v105, v82
	v_max3_f32 v251, v251, v83, v84
	v_max3_f32 v251, v251, v85, v86
	v_max3_f32 v251, v251, v87, v88
	v_max3_f32 v251, v251, v89, v89
	v_max3_f32 v13, v106, v107, v108
	v_max3_f32 v13, v13, v109, v110
	v_max3_f32 v13, v13, v111, v112
	v_max3_f32 v13, v13, v113, v90
	v_max3_f32 v13, v13, v91, v92
	v_max3_f32 v13, v13, v93, v94
	v_max3_f32 v13, v13, v95, v96
	v_max3_f32 v13, v13, v97, v97
	s_nop 1
	v_permlane32_swap_b32_e32 v251, v13
	v_max_f32_e32 v251, v251, v13
	v_mov_b32_e32 v13, v251
	s_nop 1
	v_permlane16_swap_b32_e32 v251, v13
	v_max_f32_e32 v251, v251, v13
	v_mov_b32_e32 v13, v251
	s_nop 1
	v_permlane32_swap_b32_e32 v251, v13
	v_add_f32_e32 v250, 0x41000000, v151
	v_cmp_gt_f32_e32 vcc, v251, v250
	s_cbranch_vccnz .Ldq1_p1_resc
	v_add_f32_e32 v250, 0x41000000, v161
	v_cmp_gt_f32_e32 vcc, v13, v250
	s_cbranch_vccz .Ldq1_p1_nores

.Ldq1_p1_nores:
	v_sub_f32_e32 v98, v98, v151
	v_exp_f32_e32 v98, v98
	v_sub_f32_e32 v99, v99, v151
	v_exp_f32_e32 v99, v99
	v_sub_f32_e32 v100, v100, v151
	v_exp_f32_e32 v100, v100
	v_sub_f32_e32 v101, v101, v151
	v_exp_f32_e32 v101, v101
	v_sub_f32_e32 v102, v102, v151
	v_exp_f32_e32 v102, v102
	v_sub_f32_e32 v103, v103, v151
	v_exp_f32_e32 v103, v103
	v_sub_f32_e32 v104, v104, v151
	v_exp_f32_e32 v104, v104
	v_sub_f32_e32 v105, v105, v151
	v_exp_f32_e32 v105, v105
	v_add_f32_e32 v12, v12, v98
	v_add_f32_e32 v12, v12, v99
	v_add_f32_e32 v12, v12, v100
	v_add_f32_e32 v12, v12, v101
	v_add_f32_e32 v12, v12, v102
	v_add_f32_e32 v12, v12, v103
	v_add_f32_e32 v12, v12, v104
	v_add_f32_e32 v12, v12, v105
	v_cvt_pk_bf16_f32 v98, v98, v99
	v_cvt_pk_bf16_f32 v99, v100, v101
	v_cvt_pk_bf16_f32 v100, v102, v103
	v_cvt_pk_bf16_f32 v101, v104, v105
	v_sub_f32_e32 v106, v106, v161
	v_exp_f32_e32 v106, v106
	v_sub_f32_e32 v107, v107, v161
	v_exp_f32_e32 v107, v107
	v_sub_f32_e32 v108, v108, v161
	v_exp_f32_e32 v108, v108
	v_sub_f32_e32 v109, v109, v161
	v_exp_f32_e32 v109, v109
	v_sub_f32_e32 v110, v110, v161
	v_exp_f32_e32 v110, v110
	v_sub_f32_e32 v111, v111, v161
	v_exp_f32_e32 v111, v111
	v_sub_f32_e32 v112, v112, v161
	v_exp_f32_e32 v112, v112
	v_sub_f32_e32 v113, v113, v161
	v_exp_f32_e32 v113, v113
	v_add_f32_e32 v159, v159, v106
	v_add_f32_e32 v159, v159, v107
	v_add_f32_e32 v159, v159, v108
	v_add_f32_e32 v159, v159, v109
	v_add_f32_e32 v159, v159, v110
	v_add_f32_e32 v159, v159, v111
	v_add_f32_e32 v159, v159, v112
	v_add_f32_e32 v159, v159, v113
	v_cvt_pk_bf16_f32 v106, v106, v107
	v_cvt_pk_bf16_f32 v107, v108, v109
	v_cvt_pk_bf16_f32 v108, v110, v111
	v_cvt_pk_bf16_f32 v109, v112, v113
	s_nop 1
	s_waitcnt lgkmcnt(4)
	v_mfma_f32_16x16x32_bf16 v[66:69], v[208:211], v[98:101], v[66:69]
	v_mfma_f32_16x16x32_bf16 v[70:73], v[208:211], v[106:109], v[70:73]
	ds_read_b128 v[208:211], v163 offset:55552
	v_sub_f32_e32 v82, v82, v151
	v_exp_f32_e32 v82, v82
	v_sub_f32_e32 v83, v83, v151
	v_exp_f32_e32 v83, v83
	v_sub_f32_e32 v84, v84, v151
	v_exp_f32_e32 v84, v84
	v_sub_f32_e32 v85, v85, v151
	v_exp_f32_e32 v85, v85
	s_waitcnt lgkmcnt(4)
	v_mfma_f32_16x16x32_bf16 v[74:77], v[252:255], v[98:101], v[74:77]
	v_mfma_f32_16x16x32_bf16 v[78:81], v[252:255], v[106:109], v[78:81]
	ds_read_b128 v[252:255], v163 offset:57856
	v_sub_f32_e32 v86, v86, v151
	v_exp_f32_e32 v86, v86
	v_sub_f32_e32 v87, v87, v151
	v_exp_f32_e32 v87, v87
	v_sub_f32_e32 v88, v88, v151
	v_exp_f32_e32 v88, v88
	v_sub_f32_e32 v89, v89, v151
	v_exp_f32_e32 v89, v89
	s_waitcnt lgkmcnt(4)
	v_mfma_f32_16x16x32_bf16 v[50:53], v[4:7], v[98:101], v[50:53]
	v_mfma_f32_16x16x32_bf16 v[54:57], v[4:7], v[106:109], v[54:57]
	ds_read_b128 v[4:7], v163 offset:60160
	v_add_f32_e32 v12, v12, v82
	v_add_f32_e32 v12, v12, v83
	v_add_f32_e32 v12, v12, v84
	v_add_f32_e32 v12, v12, v85
	v_add_f32_e32 v12, v12, v86
	v_add_f32_e32 v12, v12, v87
	v_add_f32_e32 v12, v12, v88
	v_add_f32_e32 v12, v12, v89
	s_waitcnt lgkmcnt(4)
	v_mfma_f32_16x16x32_bf16 v[58:61], v[8:11], v[98:101], v[58:61]
	v_mfma_f32_16x16x32_bf16 v[62:65], v[8:11], v[106:109], v[62:65]
	ds_read_b128 v[8:11], v163 offset:44096
	v_cvt_pk_bf16_f32 v82, v82, v83
	v_cvt_pk_bf16_f32 v83, v84, v85
	v_cvt_pk_bf16_f32 v84, v86, v87
	v_cvt_pk_bf16_f32 v85, v88, v89
	v_sub_f32_e32 v90, v90, v161
	v_exp_f32_e32 v90, v90
	v_sub_f32_e32 v91, v91, v161
	v_exp_f32_e32 v91, v91
	s_waitcnt lgkmcnt(4)
	v_mfma_f32_16x16x32_bf16 v[34:37], v[14:17], v[98:101], v[34:37]
	v_mfma_f32_16x16x32_bf16 v[38:41], v[14:17], v[106:109], v[38:41]
	ds_read_b128 v[14:17], v163 offset:46400
	v_sub_f32_e32 v92, v92, v161
	v_exp_f32_e32 v92, v92
	v_sub_f32_e32 v93, v93, v161
	v_exp_f32_e32 v93, v93
	v_sub_f32_e32 v94, v94, v161
	v_exp_f32_e32 v94, v94
	v_sub_f32_e32 v95, v95, v161
	v_exp_f32_e32 v95, v95
	s_waitcnt lgkmcnt(4)
	v_mfma_f32_16x16x32_bf16 v[42:45], v[208:211], v[98:101], v[42:45]
	v_mfma_f32_16x16x32_bf16 v[46:49], v[208:211], v[106:109], v[46:49]
	ds_read_b128 v[208:211], v163 offset:48704
	v_sub_f32_e32 v96, v96, v161
	v_exp_f32_e32 v96, v96
	v_sub_f32_e32 v97, v97, v161
	v_exp_f32_e32 v97, v97
	v_add_f32_e32 v159, v159, v90
	v_add_f32_e32 v159, v159, v91
	v_add_f32_e32 v159, v159, v92
	v_add_f32_e32 v159, v159, v93
	s_waitcnt lgkmcnt(4)
	v_mfma_f32_16x16x32_bf16 v[18:21], v[252:255], v[98:101], v[18:21]
	v_mfma_f32_16x16x32_bf16 v[22:25], v[252:255], v[106:109], v[22:25]
	ds_read_b128 v[252:255], v163 offset:51008
	v_add_f32_e32 v159, v159, v94
	v_add_f32_e32 v159, v159, v95
	v_add_f32_e32 v159, v159, v96
	v_add_f32_e32 v159, v159, v97
	v_cvt_pk_bf16_f32 v90, v90, v91
	v_cvt_pk_bf16_f32 v91, v92, v93
	v_cvt_pk_bf16_f32 v92, v94, v95
	v_cvt_pk_bf16_f32 v93, v96, v97
	s_waitcnt lgkmcnt(4)
	v_mfma_f32_16x16x32_bf16 v[26:29], v[4:7], v[98:101], v[26:29]
	v_mfma_f32_16x16x32_bf16 v[30:33], v[4:7], v[106:109], v[30:33]
	ds_read_b128 v[4:7], v163 offset:53312
	s_waitcnt lgkmcnt(4)
	v_mfma_f32_16x16x32_bf16 v[66:69], v[8:11], v[82:85], v[66:69]
	v_mfma_f32_16x16x32_bf16 v[70:73], v[8:11], v[90:93], v[70:73]
	ds_read_b128 v[8:11], v163 offset:55616
	s_waitcnt lgkmcnt(4)
	v_mfma_f32_16x16x32_bf16 v[74:77], v[14:17], v[82:85], v[74:77]
	v_mfma_f32_16x16x32_bf16 v[78:81], v[14:17], v[90:93], v[78:81]
	ds_read_b128 v[14:17], v163 offset:57920
	s_waitcnt lgkmcnt(4)
	v_mfma_f32_16x16x32_bf16 v[50:53], v[208:211], v[82:85], v[50:53]
	v_mfma_f32_16x16x32_bf16 v[54:57], v[208:211], v[90:93], v[54:57]
	ds_read_b128 v[208:211], v163 offset:60224
	s_waitcnt vmcnt(7)
	ds_write_b128 v168, v[212:215]
	s_waitcnt vmcnt(6)
	ds_write_b128 v170, v[216:219] offset:34816
	s_waitcnt lgkmcnt(6)
	v_mfma_f32_16x16x32_bf16 v[58:61], v[252:255], v[82:85], v[58:61]
	v_mfma_f32_16x16x32_bf16 v[62:65], v[252:255], v[90:93], v[62:65]
	s_waitcnt vmcnt(5)
	ds_write_b128 v183, v[220:223]
	s_waitcnt vmcnt(4)
	ds_write_b128 v188, v[224:227] offset:34816
	s_waitcnt lgkmcnt(7)
	v_mfma_f32_16x16x32_bf16 v[34:37], v[4:7], v[82:85], v[34:37]
	v_mfma_f32_16x16x32_bf16 v[38:41], v[4:7], v[90:93], v[38:41]
	s_waitcnt vmcnt(3)
	ds_write_b128 v190, v[228:231]
	s_waitcnt vmcnt(2)
	ds_write_b128 v193, v[232:235] offset:34816
	s_waitcnt lgkmcnt(8)
	v_mfma_f32_16x16x32_bf16 v[42:45], v[8:11], v[82:85], v[42:45]
	v_mfma_f32_16x16x32_bf16 v[46:49], v[8:11], v[90:93], v[46:49]
	s_waitcnt vmcnt(1)
	ds_write_b128 v171, v[236:239]
	s_waitcnt vmcnt(0)
	ds_write_b128 v173, v[240:243] offset:34816
	s_waitcnt lgkmcnt(9)
	v_mfma_f32_16x16x32_bf16 v[18:21], v[14:17], v[82:85], v[18:21]
	v_mfma_f32_16x16x32_bf16 v[22:25], v[14:17], v[90:93], v[22:25]
	s_waitcnt lgkmcnt(8)
	v_mfma_f32_16x16x32_bf16 v[26:29], v[208:211], v[82:85], v[26:29]
	v_mfma_f32_16x16x32_bf16 v[30:33], v[208:211], v[90:93], v[30:33]
	s_waitcnt lgkmcnt(0)
	s_barrier
	s_cmp_eq_u32 s38, s41
	s_cbranch_scc1 .Ldq1_exit
	s_mov_b32 s42, s41
	s_branch .Ldq1_p0_top
.Ldq1_exit:
	v_sub_u32_e32 v168, v168, v179
	v_lshrrev_b32_e32 v168, 1, v168
	v_sub_u32_e32 v183, v183, v179
	v_lshrrev_b32_e32 v183, 1, v183
	v_sub_u32_e32 v190, v190, v179
	v_lshrrev_b32_e32 v190, 1, v190
	v_sub_u32_e32 v171, v171, v179
	v_lshrrev_b32_e32 v171, 1, v171
	v_sub_u32_e32 v170, v170, v181
	v_sub_u32_e32 v188, v188, v181
	v_sub_u32_e32 v193, v193, v181
	v_sub_u32_e32 v173, v173, v181
	v_permlane16_swap_b32_e32 v66, v70
	v_permlane16_swap_b32_e32 v67, v71
	v_permlane16_swap_b32_e32 v68, v72
	v_permlane16_swap_b32_e32 v69, v73
	v_permlane16_swap_b32_e32 v74, v78
	v_permlane16_swap_b32_e32 v75, v79
	v_permlane16_swap_b32_e32 v76, v80
	v_permlane16_swap_b32_e32 v77, v81
	v_permlane16_swap_b32_e32 v50, v54
	v_permlane16_swap_b32_e32 v51, v55
	v_permlane16_swap_b32_e32 v52, v56
	v_permlane16_swap_b32_e32 v53, v57
	v_permlane16_swap_b32_e32 v58, v62
	v_permlane16_swap_b32_e32 v59, v63
	v_permlane16_swap_b32_e32 v60, v64
	v_permlane16_swap_b32_e32 v61, v65
	v_permlane16_swap_b32_e32 v34, v38
	v_permlane16_swap_b32_e32 v35, v39
	v_permlane16_swap_b32_e32 v36, v40
	v_permlane16_swap_b32_e32 v37, v41
	v_permlane16_swap_b32_e32 v42, v46
	v_permlane16_swap_b32_e32 v43, v47
	v_permlane16_swap_b32_e32 v44, v48
	v_permlane16_swap_b32_e32 v45, v49
	v_permlane16_swap_b32_e32 v18, v22
	v_permlane16_swap_b32_e32 v19, v23
	v_permlane16_swap_b32_e32 v20, v24
	v_permlane16_swap_b32_e32 v21, v25
	v_permlane16_swap_b32_e32 v26, v30
	v_permlane16_swap_b32_e32 v27, v31
	v_permlane16_swap_b32_e32 v28, v32
	v_permlane16_swap_b32_e32 v29, v33
	v_permlane32_swap_b32_e32 v66, v70
	v_permlane32_swap_b32_e32 v67, v71
	v_permlane32_swap_b32_e32 v68, v72
	v_permlane32_swap_b32_e32 v69, v73
	v_permlane32_swap_b32_e32 v74, v78
	v_permlane32_swap_b32_e32 v75, v79
	v_permlane32_swap_b32_e32 v76, v80
	v_permlane32_swap_b32_e32 v77, v81
	v_permlane32_swap_b32_e32 v50, v54
	v_permlane32_swap_b32_e32 v51, v55
	v_permlane32_swap_b32_e32 v52, v56
	v_permlane32_swap_b32_e32 v53, v57
	v_permlane32_swap_b32_e32 v58, v62
	v_permlane32_swap_b32_e32 v59, v63
	v_permlane32_swap_b32_e32 v60, v64
	v_permlane32_swap_b32_e32 v61, v65
	v_permlane32_swap_b32_e32 v34, v38
	v_permlane32_swap_b32_e32 v35, v39
	v_permlane32_swap_b32_e32 v36, v40
	v_permlane32_swap_b32_e32 v37, v41
	v_permlane32_swap_b32_e32 v42, v46
	v_permlane32_swap_b32_e32 v43, v47
	v_permlane32_swap_b32_e32 v44, v48
	v_permlane32_swap_b32_e32 v45, v49
	v_permlane32_swap_b32_e32 v18, v22
	v_permlane32_swap_b32_e32 v19, v23
	v_permlane32_swap_b32_e32 v20, v24
	v_permlane32_swap_b32_e32 v21, v25
	v_permlane32_swap_b32_e32 v26, v30
	v_permlane32_swap_b32_e32 v27, v31
	v_permlane32_swap_b32_e32 v28, v32
	v_permlane32_swap_b32_e32 v29, v33
	v_permlane32_swap_b32_e32 v12, v159
	v_add_f32_e32 v12, v12, v159
	v_mov_b32_e32 v159, v12
	s_nop 1
	v_permlane16_swap_b32_e32 v12, v159
	v_add_f32_e32 v12, v12, v159
	v_mov_b32_e32 v159, v12
	s_nop 1
	v_permlane32_swap_b32_e32 v12, v159
	v_and_b32_e32 v250, 16, v1
	v_cmp_ne_u32_e32 vcc, 0, v250
	v_cndmask_b32_e32 v12, v12, v159, vcc
	v_cndmask_b32_e32 v151, v151, v161, vcc
	v_and_b32_e32 v13, 32, v1
	v_cmp_eq_u32_e64 s[0:1], 0, v13
	v_cndmask_b32_e64 v12, 0, v12, s[0:1]
	v_and_b32_e32 v250, 15, v1
	v_bfe_u32 v13, v1, 5, 1
	v_lshl_add_u32 v250, v13, 4, v250
	v_lshlrev_b32_e32 v250, 2, v250
	v_add_u32_e32 v13, 0x80, v250
	ds_bpermute_b32 v4, v250, v126
	ds_bpermute_b32 v5, v250, v122
	ds_bpermute_b32 v6, v13, v126
	ds_bpermute_b32 v7, v13, v122
	s_waitcnt lgkmcnt(0)
	v_cndmask_b32_e32 v126, v4, v5, vcc
	v_cndmask_b32_e32 v122, v6, v7, vcc
	ds_bpermute_b32 v4, v250, v127
	ds_bpermute_b32 v5, v250, v123
	ds_bpermute_b32 v6, v13, v127
	ds_bpermute_b32 v7, v13, v123
	s_waitcnt lgkmcnt(0)
	v_cndmask_b32_e32 v127, v4, v5, vcc
	v_cndmask_b32_e32 v123, v6, v7, vcc
	ds_bpermute_b32 v4, v250, v128
	ds_bpermute_b32 v5, v250, v124
	ds_bpermute_b32 v6, v13, v128
	ds_bpermute_b32 v7, v13, v124
	s_waitcnt lgkmcnt(0)
	v_cndmask_b32_e32 v128, v4, v5, vcc
	v_cndmask_b32_e32 v124, v6, v7, vcc
	ds_bpermute_b32 v4, v250, v129
	ds_bpermute_b32 v5, v250, v125
	ds_bpermute_b32 v6, v13, v129
	ds_bpermute_b32 v7, v13, v125
	s_waitcnt lgkmcnt(0)
	v_cndmask_b32_e32 v129, v4, v5, vcc
	v_cndmask_b32_e32 v125, v6, v7, vcc
	ds_bpermute_b32 v4, v250, v118
	ds_bpermute_b32 v5, v250, v114
	ds_bpermute_b32 v6, v13, v118
	ds_bpermute_b32 v7, v13, v114
	s_waitcnt lgkmcnt(0)
	v_cndmask_b32_e32 v118, v4, v5, vcc
	v_cndmask_b32_e32 v114, v6, v7, vcc
	ds_bpermute_b32 v4, v250, v119
	ds_bpermute_b32 v5, v250, v115
	ds_bpermute_b32 v6, v13, v119
	ds_bpermute_b32 v7, v13, v115
	s_waitcnt lgkmcnt(0)
	v_cndmask_b32_e32 v119, v4, v5, vcc
	v_cndmask_b32_e32 v115, v6, v7, vcc
	ds_bpermute_b32 v4, v250, v120
	ds_bpermute_b32 v5, v250, v116
	ds_bpermute_b32 v6, v13, v120
	ds_bpermute_b32 v7, v13, v116
	s_waitcnt lgkmcnt(0)
	v_cndmask_b32_e32 v120, v4, v5, vcc
	v_cndmask_b32_e32 v116, v6, v7, vcc
	ds_bpermute_b32 v4, v250, v121
	ds_bpermute_b32 v5, v250, v117
	ds_bpermute_b32 v6, v13, v121
	ds_bpermute_b32 v7, v13, v117
	s_waitcnt lgkmcnt(0)
	v_cndmask_b32_e32 v121, v4, v5, vcc
	v_cndmask_b32_e32 v117, v6, v7, vcc
